# attnB loop: next-tile exps finished two MFMA gaps before the barrier
# speedup vs baseline: 1.0048x; 1.0048x over previous
.Lb_loop:
	s_waitcnt lgkmcnt(0)
	v_mfma_f32_32x32x16_bf16 v[32:47], v[192:195], v[224:227], v[32:47]
	v_mfma_f32_32x32x16_bf16 v[48:63], v[196:199], v[224:227], v[48:63]
	ds_read_b128 v[96:99], v146 offset:33280
	ds_read_b128 v[100:103], v147 offset:33280
	ds_read_b128 v[104:107], v148 offset:33280
	ds_read_b128 v[108:111], v149 offset:33280
	v_mfma_f32_32x32x16_bf16 v[16:31], v[200:203], v[224:227], v[16:31]
	v_exp_f32_e32 v240, v80
	v_exp_f32_e32 v241, v81
	v_exp_f32_e32 v242, v82
	v_mfma_f32_32x32x16_bf16 v[0:15], v[204:207], v[224:227], v[0:15]
	v_exp_f32_e32 v243, v83
	v_exp_f32_e32 v244, v84
	v_exp_f32_e32 v245, v85
	s_waitcnt lgkmcnt(0)
	v_mfma_f32_32x32x16_bf16 v[112:127], v[96:99], v[128:131], v[64:79]
	ds_read_b128 v[96:99], v146 offset:37376
	ds_read_b64_tr_b16 v[192:193], v179 offset:18688
	ds_read_b64_tr_b16 v[194:195], v179 offset:19200
	v_add_f32_e32 v145, v240, v241
	v_cvt_pk_bf16_f32 v232, v240, v241
	v_exp_f32_e32 v246, v86
	v_exp_f32_e32 v247, v87
	v_mfma_f32_32x32x16_bf16 v[112:127], v[100:103], v[132:135], v[112:127]
	ds_read_b128 v[100:103], v147 offset:37376
	ds_read_b64_tr_b16 v[196:197], v179 offset:22848
	ds_read_b64_tr_b16 v[198:199], v179 offset:23360
	s_add_i32 s0, s50, 0xffff8000
	s_and_b32 s0, s0, 0x1f8000
	s_lshl_b32 s4, s0, 1
	s_add_i32 m0, s41, 0x18600
	s_nop 0
	buffer_load_dwordx4 v250, s[8:11], s4 offen lds
	s_add_i32 m0, s41, 0x1a600
	s_nop 0
	buffer_load_dwordx4 v250, s[8:11], s4 offen offset:128 lds
	v_add_f32_e32 v145, v145, v242
	v_add_f32_e32 v145, v145, v243
	v_cvt_pk_bf16_f32 v233, v242, v243
	v_exp_f32_e32 v240, v88
	v_mfma_f32_32x32x16_bf16 v[112:127], v[104:107], v[136:139], v[112:127]
	ds_read_b128 v[104:107], v148 offset:37376
	ds_read_b64_tr_b16 v[200:201], v179 offset:27008
	ds_read_b64_tr_b16 v[202:203], v179 offset:27520
	v_exp_f32_e32 v241, v89
	v_add_f32_e32 v145, v145, v244
	v_add_f32_e32 v145, v145, v245
	v_cvt_pk_bf16_f32 v234, v244, v245
	v_exp_f32_e32 v242, v90
	v_mfma_f32_32x32x16_bf16 v[112:127], v[108:111], v[140:143], v[112:127]
	ds_read_b128 v[108:111], v149 offset:37376
	ds_read_b64_tr_b16 v[204:205], v179 offset:31168
	ds_read_b64_tr_b16 v[206:207], v179 offset:31680
	s_add_i32 m0, s43, 0x18600
	s_nop 0
	buffer_load_dwordx4 v251, s[12:15], s4 offen lds
	s_add_i32 m0, s43, 0x1a600
	s_nop 0
	buffer_load_dwordx4 v251, s[12:15], s4 offen offset:128 lds
	v_exp_f32_e32 v243, v91
	v_add_f32_e32 v145, v145, v246
	v_add_f32_e32 v145, v145, v247
	v_cvt_pk_bf16_f32 v235, v246, v247
	v_mfma_f32_32x32x16_bf16 v[32:47], v[208:211], v[228:231], v[32:47]
	ds_read_b64_tr_b16 v[208:209], v179 offset:19712
	ds_read_b64_tr_b16 v[210:211], v179 offset:20224
	v_exp_f32_e32 v244, v92
	v_exp_f32_e32 v245, v93
	v_add_f32_e32 v145, v145, v240
	v_add_f32_e32 v145, v145, v241
	v_mfma_f32_32x32x16_bf16 v[48:63], v[212:215], v[228:231], v[48:63]
	ds_read_b64_tr_b16 v[212:213], v179 offset:23872
	ds_read_b64_tr_b16 v[214:215], v179 offset:24384
	v_cvt_pk_bf16_f32 v236, v240, v241
	v_exp_f32_e32 v246, v94
	v_exp_f32_e32 v247, v95
	v_mfma_f32_32x32x16_bf16 v[16:31], v[216:219], v[228:231], v[16:31]
	ds_read_b64_tr_b16 v[216:217], v179 offset:28032
	ds_read_b64_tr_b16 v[218:219], v179 offset:28544
	v_add_f32_e32 v145, v145, v242
	v_add_f32_e32 v145, v145, v243
	v_cvt_pk_bf16_f32 v237, v242, v243
	v_add_f32_e32 v145, v145, v244
	v_add_f32_e32 v145, v145, v245
	v_cvt_pk_bf16_f32 v238, v244, v245
	v_mfma_f32_32x32x16_bf16 v[0:15], v[220:223], v[228:231], v[0:15]
	ds_read_b64_tr_b16 v[220:221], v179 offset:32192
	ds_read_b64_tr_b16 v[222:223], v179 offset:32704
	v_add_f32_e32 v145, v145, v246
	v_add_f32_e32 v249, v145, v247
	v_cvt_pk_bf16_f32 v239, v246, v247
	v_add_f32_e32 v249, v248, v249
	v_cmp_lt_f32_e32 vcc, s3, v249
	v_add_f32_e32 v191, v191, v249
	s_waitcnt lgkmcnt(8)
	v_mfma_f32_32x32x16_bf16 v[80:95], v[96:99], v[128:131], v[64:79]
	v_exp_f32_e32 v240, v112
	v_exp_f32_e32 v241, v113
	v_exp_f32_e32 v242, v114
	v_mfma_f32_32x32x16_bf16 v[80:95], v[100:103], v[132:135], v[80:95]
	v_exp_f32_e32 v243, v115
	v_exp_f32_e32 v244, v116
	v_exp_f32_e32 v245, v117
	v_mfma_f32_32x32x16_bf16 v[80:95], v[104:107], v[136:139], v[80:95]
	v_add_f32_e32 v145, v240, v241
	v_cvt_pk_bf16_f32 v224, v240, v241
	v_exp_f32_e32 v246, v118
	v_mfma_f32_32x32x16_bf16 v[80:95], v[108:111], v[140:143], v[80:95]
	v_exp_f32_e32 v247, v119
	v_add_f32_e32 v145, v145, v242
	v_add_f32_e32 v145, v145, v243
	v_cvt_pk_bf16_f32 v225, v242, v243
	v_exp_f32_e32 v240, v120
	v_mfma_f32_32x32x16_bf16 v[32:47], v[192:195], v[232:235], v[32:47]
	ds_read_b64_tr_b16 v[192:193], v180 offset:0
	ds_read_b64_tr_b16 v[194:195], v180 offset:512
	v_exp_f32_e32 v241, v121
	v_add_f32_e32 v145, v145, v244
	v_add_f32_e32 v145, v145, v245
	v_cvt_pk_bf16_f32 v226, v244, v245
	v_mfma_f32_32x32x16_bf16 v[48:63], v[196:199], v[232:235], v[48:63]
	ds_read_b64_tr_b16 v[196:197], v180 offset:4160
	ds_read_b64_tr_b16 v[198:199], v180 offset:4672
	v_exp_f32_e32 v242, v122
	v_exp_f32_e32 v243, v123
	v_add_f32_e32 v145, v145, v246
	v_mfma_f32_32x32x16_bf16 v[16:31], v[200:203], v[232:235], v[16:31]
	ds_read_b64_tr_b16 v[200:201], v180 offset:8320
	ds_read_b64_tr_b16 v[202:203], v180 offset:8832
	v_add_f32_e32 v145, v145, v247
	v_cvt_pk_bf16_f32 v227, v246, v247
	v_exp_f32_e32 v244, v124
	v_exp_f32_e32 v245, v125
	v_mfma_f32_32x32x16_bf16 v[0:15], v[204:207], v[232:235], v[0:15]
	ds_read_b64_tr_b16 v[204:205], v180 offset:12480
	ds_read_b64_tr_b16 v[206:207], v180 offset:12992
	v_add_f32_e32 v145, v145, v240
	v_add_f32_e32 v145, v145, v241
	v_cvt_pk_bf16_f32 v228, v240, v241
	v_exp_f32_e32 v246, v126
	s_waitcnt lgkmcnt(8)
	v_mfma_f32_32x32x16_bf16 v[32:47], v[208:211], v[236:239], v[32:47]
	ds_read_b64_tr_b16 v[208:209], v180 offset:1024
	ds_read_b64_tr_b16 v[210:211], v180 offset:1536
	v_exp_f32_e32 v247, v127
	v_add_f32_e32 v145, v145, v242
	v_add_f32_e32 v145, v145, v243
	v_cvt_pk_bf16_f32 v229, v242, v243
	v_add_f32_e32 v145, v145, v244
	v_mfma_f32_32x32x16_bf16 v[48:63], v[212:215], v[236:239], v[48:63]
	ds_read_b64_tr_b16 v[212:213], v180 offset:5184
	ds_read_b64_tr_b16 v[214:215], v180 offset:5696
	v_add_f32_e32 v145, v145, v245
	v_cvt_pk_bf16_f32 v230, v244, v245
	v_add_f32_e32 v145, v145, v246
	v_add_f32_e32 v248, v145, v247
	v_cvt_pk_bf16_f32 v231, v246, v247
	v_mfma_f32_32x32x16_bf16 v[16:31], v[216:219], v[236:239], v[16:31]
	ds_read_b64_tr_b16 v[216:217], v180 offset:9344
	ds_read_b64_tr_b16 v[218:219], v180 offset:9856
	v_mfma_f32_32x32x16_bf16 v[0:15], v[220:223], v[236:239], v[0:15]
	ds_read_b64_tr_b16 v[220:221], v180 offset:13504
	ds_read_b64_tr_b16 v[222:223], v180 offset:14016
	s_cbranch_vccz .Lb_cont0
	s_branch .Lb_rare0

.Lb_pn3:
	v_exp_f32_e32 v243, v91
	v_add_f32_e32 v145, v145, v246
	v_add_f32_e32 v145, v145, v247
	v_cvt_pk_bf16_f32 v235, v246, v247
	v_mfma_f32_32x32x16_bf16 v[32:47], v[208:211], v[228:231], v[32:47]
	ds_read_b64_tr_b16 v[208:209], v180 offset:3072
	ds_read_b64_tr_b16 v[210:211], v180 offset:3584
	v_exp_f32_e32 v244, v92
	v_exp_f32_e32 v245, v93
	v_add_f32_e32 v145, v145, v240
	v_add_f32_e32 v145, v145, v241
	v_mfma_f32_32x32x16_bf16 v[48:63], v[212:215], v[228:231], v[48:63]
	ds_read_b64_tr_b16 v[212:213], v180 offset:7232
	ds_read_b64_tr_b16 v[214:215], v180 offset:7744
	v_cvt_pk_bf16_f32 v236, v240, v241
	v_exp_f32_e32 v246, v94
	v_exp_f32_e32 v247, v95
	v_mfma_f32_32x32x16_bf16 v[16:31], v[216:219], v[228:231], v[16:31]
	ds_read_b64_tr_b16 v[216:217], v180 offset:11392
	ds_read_b64_tr_b16 v[218:219], v180 offset:11904
	v_add_f32_e32 v145, v145, v242
	v_add_f32_e32 v145, v145, v243
	v_cvt_pk_bf16_f32 v237, v242, v243
	v_add_f32_e32 v145, v145, v244
	v_add_f32_e32 v145, v145, v245
	v_cvt_pk_bf16_f32 v238, v244, v245
	v_mfma_f32_32x32x16_bf16 v[0:15], v[220:223], v[228:231], v[0:15]
	ds_read_b64_tr_b16 v[220:221], v180 offset:15552
	ds_read_b64_tr_b16 v[222:223], v180 offset:16064
	v_add_f32_e32 v145, v145, v246
	v_add_f32_e32 v249, v145, v247
	v_cvt_pk_bf16_f32 v239, v246, v247
	v_add_f32_e32 v249, v248, v249
	v_cmp_lt_f32_e32 vcc, s3, v249
	v_add_f32_e32 v191, v191, v249
	s_waitcnt lgkmcnt(8)
	v_mfma_f32_32x32x16_bf16 v[80:95], v[96:99], v[128:131], v[64:79]
	v_exp_f32_e32 v240, v112
	v_exp_f32_e32 v241, v113
	v_exp_f32_e32 v242, v114
	v_mfma_f32_32x32x16_bf16 v[80:95], v[100:103], v[132:135], v[80:95]
	v_exp_f32_e32 v243, v115
	v_exp_f32_e32 v244, v116
	v_exp_f32_e32 v245, v117
	v_mfma_f32_32x32x16_bf16 v[80:95], v[104:107], v[136:139], v[80:95]
	v_add_f32_e32 v145, v240, v241
	v_cvt_pk_bf16_f32 v224, v240, v241
	v_exp_f32_e32 v246, v118
	v_mfma_f32_32x32x16_bf16 v[80:95], v[108:111], v[140:143], v[80:95]
	v_exp_f32_e32 v247, v119
	v_add_f32_e32 v145, v145, v242
	v_add_f32_e32 v145, v145, v243
	v_cvt_pk_bf16_f32 v225, v242, v243
	v_exp_f32_e32 v240, v120
	v_mfma_f32_32x32x16_bf16 v[32:47], v[192:195], v[232:235], v[32:47]
	ds_read_b64_tr_b16 v[192:193], v182 offset:0
	ds_read_b64_tr_b16 v[194:195], v182 offset:512
	v_exp_f32_e32 v241, v121
	v_add_f32_e32 v145, v145, v244
	v_add_f32_e32 v145, v145, v245
	v_cvt_pk_bf16_f32 v226, v244, v245
	v_mfma_f32_32x32x16_bf16 v[48:63], v[196:199], v[232:235], v[48:63]
	ds_read_b64_tr_b16 v[196:197], v182 offset:4160
	ds_read_b64_tr_b16 v[198:199], v182 offset:4672
	v_exp_f32_e32 v242, v122
	v_exp_f32_e32 v243, v123
	v_add_f32_e32 v145, v145, v246
	v_mfma_f32_32x32x16_bf16 v[16:31], v[200:203], v[232:235], v[16:31]
	ds_read_b64_tr_b16 v[200:201], v182 offset:8320
	ds_read_b64_tr_b16 v[202:203], v182 offset:8832
	v_add_f32_e32 v145, v145, v247
	v_cvt_pk_bf16_f32 v227, v246, v247
	v_exp_f32_e32 v244, v124
	v_exp_f32_e32 v245, v125
	v_mfma_f32_32x32x16_bf16 v[0:15], v[204:207], v[232:235], v[0:15]
	ds_read_b64_tr_b16 v[204:205], v182 offset:12480
	ds_read_b64_tr_b16 v[206:207], v182 offset:12992
	v_add_f32_e32 v145, v145, v240
	v_add_f32_e32 v145, v145, v241
	v_cvt_pk_bf16_f32 v228, v240, v241
	v_exp_f32_e32 v246, v126
	s_waitcnt lgkmcnt(8)
	v_mfma_f32_32x32x16_bf16 v[32:47], v[208:211], v[236:239], v[32:47]
	ds_read_b64_tr_b16 v[208:209], v182 offset:1024
	ds_read_b64_tr_b16 v[210:211], v182 offset:1536
	v_exp_f32_e32 v247, v127
	v_add_f32_e32 v145, v145, v242
	v_add_f32_e32 v145, v145, v243
	v_cvt_pk_bf16_f32 v229, v242, v243
	v_add_f32_e32 v145, v145, v244
	v_mfma_f32_32x32x16_bf16 v[48:63], v[212:215], v[236:239], v[48:63]
	ds_read_b64_tr_b16 v[212:213], v182 offset:5184
	ds_read_b64_tr_b16 v[214:215], v182 offset:5696
	v_add_f32_e32 v145, v145, v245
	v_cvt_pk_bf16_f32 v230, v244, v245
	v_add_f32_e32 v145, v145, v246
	v_add_f32_e32 v248, v145, v247
	v_cvt_pk_bf16_f32 v231, v246, v247
	v_mfma_f32_32x32x16_bf16 v[16:31], v[216:219], v[236:239], v[16:31]
	ds_read_b64_tr_b16 v[216:217], v182 offset:9344
	ds_read_b64_tr_b16 v[218:219], v182 offset:9856
	v_mfma_f32_32x32x16_bf16 v[0:15], v[220:223], v[236:239], v[0:15]
	ds_read_b64_tr_b16 v[220:221], v182 offset:13504
	ds_read_b64_tr_b16 v[222:223], v182 offset:14016
	s_cbranch_vccz .Lb_cont1
	s_branch .Lb_rare1

.Lb_pn7:
	v_exp_f32_e32 v243, v91
	v_add_f32_e32 v145, v145, v246
	v_add_f32_e32 v145, v145, v247
	v_cvt_pk_bf16_f32 v235, v246, v247
	v_mfma_f32_32x32x16_bf16 v[32:47], v[208:211], v[228:231], v[32:47]
	ds_read_b64_tr_b16 v[208:209], v182 offset:3072
	ds_read_b64_tr_b16 v[210:211], v182 offset:3584
	v_exp_f32_e32 v244, v92
	v_exp_f32_e32 v245, v93
	v_add_f32_e32 v145, v145, v240
	v_add_f32_e32 v145, v145, v241
	v_mfma_f32_32x32x16_bf16 v[48:63], v[212:215], v[228:231], v[48:63]
	ds_read_b64_tr_b16 v[212:213], v182 offset:7232
	ds_read_b64_tr_b16 v[214:215], v182 offset:7744
	v_cvt_pk_bf16_f32 v236, v240, v241
	v_exp_f32_e32 v246, v94
	v_exp_f32_e32 v247, v95
	v_mfma_f32_32x32x16_bf16 v[16:31], v[216:219], v[228:231], v[16:31]
	ds_read_b64_tr_b16 v[216:217], v182 offset:11392
	ds_read_b64_tr_b16 v[218:219], v182 offset:11904
	v_add_f32_e32 v145, v145, v242
	v_add_f32_e32 v145, v145, v243
	v_cvt_pk_bf16_f32 v237, v242, v243
	v_add_f32_e32 v145, v145, v244
	v_add_f32_e32 v145, v145, v245
	v_cvt_pk_bf16_f32 v238, v244, v245
	v_mfma_f32_32x32x16_bf16 v[0:15], v[220:223], v[228:231], v[0:15]
	ds_read_b64_tr_b16 v[220:221], v182 offset:15552
	ds_read_b64_tr_b16 v[222:223], v182 offset:16064
	v_add_f32_e32 v145, v145, v246
	v_add_f32_e32 v249, v145, v247
	v_cvt_pk_bf16_f32 v239, v246, v247
	v_add_f32_e32 v249, v248, v249
	v_cmp_lt_f32_e32 vcc, s3, v249
	v_add_f32_e32 v191, v191, v249
	s_waitcnt lgkmcnt(8)
	v_mfma_f32_32x32x16_bf16 v[80:95], v[96:99], v[128:131], v[64:79]
	v_exp_f32_e32 v240, v112
	v_exp_f32_e32 v241, v113
	v_exp_f32_e32 v242, v114
	v_mfma_f32_32x32x16_bf16 v[80:95], v[100:103], v[132:135], v[80:95]
	v_exp_f32_e32 v243, v115
	v_exp_f32_e32 v244, v116
	v_exp_f32_e32 v245, v117
	v_mfma_f32_32x32x16_bf16 v[80:95], v[104:107], v[136:139], v[80:95]
	v_add_f32_e32 v145, v240, v241
	v_cvt_pk_bf16_f32 v224, v240, v241
	v_exp_f32_e32 v246, v118
	v_mfma_f32_32x32x16_bf16 v[80:95], v[108:111], v[140:143], v[80:95]
	v_exp_f32_e32 v247, v119
	v_add_f32_e32 v145, v145, v242
	v_add_f32_e32 v145, v145, v243
	v_cvt_pk_bf16_f32 v225, v242, v243
	v_exp_f32_e32 v240, v120
	v_mfma_f32_32x32x16_bf16 v[32:47], v[192:195], v[232:235], v[32:47]
	ds_read_b64_tr_b16 v[192:193], v182 offset:33280
	ds_read_b64_tr_b16 v[194:195], v182 offset:33792
	v_exp_f32_e32 v241, v121
	v_add_f32_e32 v145, v145, v244
	v_add_f32_e32 v145, v145, v245
	v_cvt_pk_bf16_f32 v226, v244, v245
	v_mfma_f32_32x32x16_bf16 v[48:63], v[196:199], v[232:235], v[48:63]
	ds_read_b64_tr_b16 v[196:197], v182 offset:37440
	ds_read_b64_tr_b16 v[198:199], v182 offset:37952
	v_exp_f32_e32 v242, v122
	v_exp_f32_e32 v243, v123
	v_add_f32_e32 v145, v145, v246
	v_mfma_f32_32x32x16_bf16 v[16:31], v[200:203], v[232:235], v[16:31]
	ds_read_b64_tr_b16 v[200:201], v182 offset:41600
	ds_read_b64_tr_b16 v[202:203], v182 offset:42112
	v_add_f32_e32 v145, v145, v247
	v_cvt_pk_bf16_f32 v227, v246, v247
	v_exp_f32_e32 v244, v124
	v_exp_f32_e32 v245, v125
	v_mfma_f32_32x32x16_bf16 v[0:15], v[204:207], v[232:235], v[0:15]
	ds_read_b64_tr_b16 v[204:205], v182 offset:45760
	ds_read_b64_tr_b16 v[206:207], v182 offset:46272
	v_add_f32_e32 v145, v145, v240
	v_add_f32_e32 v145, v145, v241
	v_cvt_pk_bf16_f32 v228, v240, v241
	v_exp_f32_e32 v246, v126
	s_waitcnt lgkmcnt(8)
	v_mfma_f32_32x32x16_bf16 v[32:47], v[208:211], v[236:239], v[32:47]
	ds_read_b64_tr_b16 v[208:209], v182 offset:34304
	ds_read_b64_tr_b16 v[210:211], v182 offset:34816
	v_exp_f32_e32 v247, v127
	v_add_f32_e32 v145, v145, v242
	v_add_f32_e32 v145, v145, v243
	v_cvt_pk_bf16_f32 v229, v242, v243
	v_add_f32_e32 v145, v145, v244
	v_mfma_f32_32x32x16_bf16 v[48:63], v[212:215], v[236:239], v[48:63]
	ds_read_b64_tr_b16 v[212:213], v182 offset:38464
	ds_read_b64_tr_b16 v[214:215], v182 offset:38976
	v_add_f32_e32 v145, v145, v245
	v_cvt_pk_bf16_f32 v230, v244, v245
	v_add_f32_e32 v145, v145, v246
	v_add_f32_e32 v248, v145, v247
	v_cvt_pk_bf16_f32 v231, v246, v247
	v_mfma_f32_32x32x16_bf16 v[16:31], v[216:219], v[236:239], v[16:31]
	ds_read_b64_tr_b16 v[216:217], v182 offset:42624
	ds_read_b64_tr_b16 v[218:219], v182 offset:43136
	v_mfma_f32_32x32x16_bf16 v[0:15], v[220:223], v[236:239], v[0:15]
	ds_read_b64_tr_b16 v[220:221], v182 offset:46784
	ds_read_b64_tr_b16 v[222:223], v182 offset:47296
	s_cbranch_vccz .Lb_cont2
	s_branch .Lb_rare2
.Lb_cont2:
	s_waitcnt vmcnt(4)
	s_barrier
	s_cmp_gt_u32 s6, 59
	s_cbranch_scc1 .Lb_final
	s_waitcnt lgkmcnt(0)
	v_mfma_f32_32x32x16_bf16 v[32:47], v[192:195], v[224:227], v[32:47]
	v_mfma_f32_32x32x16_bf16 v[48:63], v[196:199], v[224:227], v[48:63]
	ds_read_b128 v[96:99], v146 offset:0
	ds_read_b128 v[100:103], v147 offset:0
	ds_read_b128 v[104:107], v148 offset:0
	ds_read_b128 v[108:111], v149 offset:0
	v_mfma_f32_32x32x16_bf16 v[16:31], v[200:203], v[224:227], v[16:31]
	v_exp_f32_e32 v240, v80
	v_exp_f32_e32 v241, v81
	v_exp_f32_e32 v242, v82
	v_mfma_f32_32x32x16_bf16 v[0:15], v[204:207], v[224:227], v[0:15]
	v_exp_f32_e32 v243, v83
	v_exp_f32_e32 v244, v84
	v_exp_f32_e32 v245, v85
	s_waitcnt lgkmcnt(0)
	v_mfma_f32_32x32x16_bf16 v[112:127], v[96:99], v[128:131], v[64:79]
	ds_read_b128 v[96:99], v146 offset:4096
	ds_read_b64_tr_b16 v[192:193], v182 offset:35328
	ds_read_b64_tr_b16 v[194:195], v182 offset:35840
	v_add_f32_e32 v145, v240, v241
	v_cvt_pk_bf16_f32 v232, v240, v241
	v_exp_f32_e32 v246, v86
	v_exp_f32_e32 v247, v87
	v_mfma_f32_32x32x16_bf16 v[112:127], v[100:103], v[132:135], v[112:127]
	ds_read_b128 v[100:103], v147 offset:4096
	ds_read_b64_tr_b16 v[196:197], v182 offset:39488
	ds_read_b64_tr_b16 v[198:199], v182 offset:40000
	s_add_i32 s0, s50, 0x10000
	s_and_b32 s0, s0, 0x1f8000
	s_lshl_b32 s4, s0, 1
	s_add_i32 m0, s41, 0x10400
	s_nop 0
	buffer_load_dwordx4 v250, s[8:11], s4 offen lds
	s_add_i32 m0, s41, 0x12400
	s_nop 0
	buffer_load_dwordx4 v250, s[8:11], s4 offen offset:128 lds
	v_add_f32_e32 v145, v145, v242
	v_add_f32_e32 v145, v145, v243
	v_cvt_pk_bf16_f32 v233, v242, v243
	v_exp_f32_e32 v240, v88
	v_mfma_f32_32x32x16_bf16 v[112:127], v[104:107], v[136:139], v[112:127]
	ds_read_b128 v[104:107], v148 offset:4096
	ds_read_b64_tr_b16 v[200:201], v182 offset:43648
	ds_read_b64_tr_b16 v[202:203], v182 offset:44160
	v_exp_f32_e32 v241, v89
	v_add_f32_e32 v145, v145, v244
	v_add_f32_e32 v145, v145, v245
	v_cvt_pk_bf16_f32 v234, v244, v245
	v_exp_f32_e32 v242, v90
	v_mfma_f32_32x32x16_bf16 v[112:127], v[108:111], v[140:143], v[112:127]
	ds_read_b128 v[108:111], v149 offset:4096
	ds_read_b64_tr_b16 v[204:205], v182 offset:47808
	ds_read_b64_tr_b16 v[206:207], v182 offset:48320
	s_add_i32 m0, s43, 0x10400
	s_nop 0
	buffer_load_dwordx4 v251, s[12:15], s4 offen lds
	s_add_i32 m0, s43, 0x12400
	s_nop 0
	buffer_load_dwordx4 v251, s[12:15], s4 offen offset:128 lds
	v_exp_f32_e32 v243, v91
	v_add_f32_e32 v145, v145, v246
	v_add_f32_e32 v145, v145, v247
	v_cvt_pk_bf16_f32 v235, v246, v247
	v_mfma_f32_32x32x16_bf16 v[32:47], v[208:211], v[228:231], v[32:47]
	ds_read_b64_tr_b16 v[208:209], v182 offset:36352
	ds_read_b64_tr_b16 v[210:211], v182 offset:36864
	v_exp_f32_e32 v244, v92
	v_exp_f32_e32 v245, v93
	v_add_f32_e32 v145, v145, v240
	v_add_f32_e32 v145, v145, v241
	v_mfma_f32_32x32x16_bf16 v[48:63], v[212:215], v[228:231], v[48:63]
	ds_read_b64_tr_b16 v[212:213], v182 offset:40512
	ds_read_b64_tr_b16 v[214:215], v182 offset:41024
	v_cvt_pk_bf16_f32 v236, v240, v241
	v_exp_f32_e32 v246, v94
	v_exp_f32_e32 v247, v95
	v_mfma_f32_32x32x16_bf16 v[16:31], v[216:219], v[228:231], v[16:31]
	ds_read_b64_tr_b16 v[216:217], v182 offset:44672
	ds_read_b64_tr_b16 v[218:219], v182 offset:45184
	v_add_f32_e32 v145, v145, v242
	v_add_f32_e32 v145, v145, v243
	v_cvt_pk_bf16_f32 v237, v242, v243
	v_add_f32_e32 v145, v145, v244
	v_add_f32_e32 v145, v145, v245
	v_cvt_pk_bf16_f32 v238, v244, v245
	v_mfma_f32_32x32x16_bf16 v[0:15], v[220:223], v[228:231], v[0:15]
	ds_read_b64_tr_b16 v[220:221], v182 offset:48832
	ds_read_b64_tr_b16 v[222:223], v182 offset:49344
	v_add_f32_e32 v145, v145, v246
	v_add_f32_e32 v249, v145, v247
	v_cvt_pk_bf16_f32 v239, v246, v247
	v_add_f32_e32 v249, v248, v249
	v_cmp_lt_f32_e32 vcc, s3, v249
	v_add_f32_e32 v191, v191, v249
	s_waitcnt lgkmcnt(8)
	v_mfma_f32_32x32x16_bf16 v[80:95], v[96:99], v[128:131], v[64:79]
	v_exp_f32_e32 v240, v112
	v_exp_f32_e32 v241, v113
	v_exp_f32_e32 v242, v114
	v_mfma_f32_32x32x16_bf16 v[80:95], v[100:103], v[132:135], v[80:95]
	v_exp_f32_e32 v243, v115
	v_exp_f32_e32 v244, v116
	v_exp_f32_e32 v245, v117
	v_mfma_f32_32x32x16_bf16 v[80:95], v[104:107], v[136:139], v[80:95]
	v_add_f32_e32 v145, v240, v241
	v_cvt_pk_bf16_f32 v224, v240, v241
	v_exp_f32_e32 v246, v118
	v_mfma_f32_32x32x16_bf16 v[80:95], v[108:111], v[140:143], v[80:95]
	v_exp_f32_e32 v247, v119
	v_add_f32_e32 v145, v145, v242
	v_add_f32_e32 v145, v145, v243
	v_cvt_pk_bf16_f32 v225, v242, v243
	v_exp_f32_e32 v240, v120
	v_mfma_f32_32x32x16_bf16 v[32:47], v[192:195], v[232:235], v[32:47]
	ds_read_b64_tr_b16 v[192:193], v179 offset:16640
	ds_read_b64_tr_b16 v[194:195], v179 offset:17152
	v_exp_f32_e32 v241, v121
	v_add_f32_e32 v145, v145, v244
	v_add_f32_e32 v145, v145, v245
	v_cvt_pk_bf16_f32 v226, v244, v245
	v_mfma_f32_32x32x16_bf16 v[48:63], v[196:199], v[232:235], v[48:63]
	ds_read_b64_tr_b16 v[196:197], v179 offset:20800
	ds_read_b64_tr_b16 v[198:199], v179 offset:21312
	v_exp_f32_e32 v242, v122
	v_exp_f32_e32 v243, v123
	v_add_f32_e32 v145, v145, v246
	v_mfma_f32_32x32x16_bf16 v[16:31], v[200:203], v[232:235], v[16:31]
	ds_read_b64_tr_b16 v[200:201], v179 offset:24960
	ds_read_b64_tr_b16 v[202:203], v179 offset:25472
	v_add_f32_e32 v145, v145, v247
	v_cvt_pk_bf16_f32 v227, v246, v247
	v_exp_f32_e32 v244, v124
	v_exp_f32_e32 v245, v125
	v_mfma_f32_32x32x16_bf16 v[0:15], v[204:207], v[232:235], v[0:15]
	ds_read_b64_tr_b16 v[204:205], v179 offset:29120
	ds_read_b64_tr_b16 v[206:207], v179 offset:29632
	v_add_f32_e32 v145, v145, v240
	v_add_f32_e32 v145, v145, v241
	v_cvt_pk_bf16_f32 v228, v240, v241
	v_exp_f32_e32 v246, v126
	s_waitcnt lgkmcnt(8)
	v_mfma_f32_32x32x16_bf16 v[32:47], v[208:211], v[236:239], v[32:47]
	ds_read_b64_tr_b16 v[208:209], v179 offset:17664
	ds_read_b64_tr_b16 v[210:211], v179 offset:18176
	v_exp_f32_e32 v247, v127
	v_add_f32_e32 v145, v145, v242
	v_add_f32_e32 v145, v145, v243
	v_cvt_pk_bf16_f32 v229, v242, v243
	v_add_f32_e32 v145, v145, v244
	v_mfma_f32_32x32x16_bf16 v[48:63], v[212:215], v[236:239], v[48:63]
	ds_read_b64_tr_b16 v[212:213], v179 offset:21824
	ds_read_b64_tr_b16 v[214:215], v179 offset:22336
	v_add_f32_e32 v145, v145, v245
	v_cvt_pk_bf16_f32 v230, v244, v245
	v_add_f32_e32 v145, v145, v246
	v_add_f32_e32 v248, v145, v247
	v_cvt_pk_bf16_f32 v231, v246, v247
	v_mfma_f32_32x32x16_bf16 v[16:31], v[216:219], v[236:239], v[16:31]
	ds_read_b64_tr_b16 v[216:217], v179 offset:25984
	ds_read_b64_tr_b16 v[218:219], v179 offset:26496
	v_mfma_f32_32x32x16_bf16 v[0:15], v[220:223], v[236:239], v[0:15]
	ds_read_b64_tr_b16 v[220:221], v179 offset:30144
	ds_read_b64_tr_b16 v[222:223], v179 offset:30656
	s_cbranch_vccz .Lb_cont3
	s_branch .Lb_rare3
